# plus: attention row-max tree from max3 and paired score moves, rpb LDS reads batched, spatial u-tile loads widened to dwordx4
# speedup vs baseline: 1.0204x; 1.0043x over previous
.LBB0_675:
	s_and_b32 s0, s4, 0xffffff80
	s_and_b32 s2, s6, 7
	s_ashr_i32 s1, s0, 31
	v_lshl_add_u32 v6, s2, 8, v117
	v_lshl_add_u64 v[2:3], s[0:1], 1, v[70:71]
	v_mad_i64_i32 v[4:5], s[8:9], v6, s7, v[2:3]
	global_load_dwordx4 v[38:41], v[4:5], off
	v_add_u32_e32 v4, 32, v6
	v_mad_i64_i32 v[4:5], s[8:9], v4, s7, v[2:3]
	global_load_dwordx4 v[42:45], v[4:5], off
	v_add_u32_e32 v4, 64, v6
	v_mad_i64_i32 v[4:5], s[8:9], v4, s7, v[2:3]
	global_load_dwordx4 v[46:49], v[4:5], off
	v_add_u32_e32 v4, 0x60, v6
	v_mad_i64_i32 v[4:5], s[8:9], v4, s7, v[2:3]
	global_load_dwordx4 v[50:53], v[4:5], off
	v_add_u32_e32 v4, 0x80, v6
	v_mad_i64_i32 v[4:5], s[8:9], v4, s7, v[2:3]
	global_load_dwordx4 v[54:57], v[4:5], off
	v_add_u32_e32 v4, 0xa0, v6
	v_mad_i64_i32 v[4:5], s[8:9], v4, s7, v[2:3]
	global_load_dwordx4 v[58:61], v[4:5], off
	v_add_u32_e32 v4, 0xc0, v6
	v_mad_i64_i32 v[4:5], s[8:9], v4, s7, v[2:3]
	global_load_dwordx4 v[62:65], v[4:5], off
	v_add_u32_e32 v4, 0xe0, v6
	v_mad_i64_i32 v[2:3], s[8:9], v4, s7, v[2:3]
	v_lshl_add_u64 v[34:35], s[0:1], 2, v[76:77]
	global_load_dwordx4 v[66:69], v[2:3], off
	s_lshl_b32 s30, s2, 7
	global_load_dwordx4 v[34:37], v[34:35], off
	v_lshl_add_u64 v[2:3], s[30:31], 0, v[72:73]
	v_lshlrev_b64 v[2:3], 9, v[2:3]
	v_lshl_add_u64 v[2:3], v[74:75], 0, v[2:3]
	s_movk_i32 s3, 0x2000
	v_add_co_u32_e32 v4, vcc, s3, v2
	s_movk_i32 s3, 0x4000
	s_nop 0
	v_addc_co_u32_e32 v5, vcc, 0, v3, vcc
	global_load_dwordx4 v[6:9], v[2:3], off
	global_load_dwordx4 v[30:33], v[4:5], off
	v_add_co_u32_e32 v4, vcc, s3, v2
	s_mov_b32 s3, 0x8000
	s_nop 0
	v_addc_co_u32_e32 v5, vcc, 0, v3, vcc
	global_load_dwordx4 v[26:29], v[4:5], off
	v_add_co_u32_e32 v4, vcc, s7, v2
	v_or_b32_e32 v82, s0, v116
	s_nop 0
	v_addc_co_u32_e32 v5, vcc, 0, v3, vcc
	global_load_dwordx4 v[22:25], v[4:5], off
	v_add_co_u32_e32 v4, vcc, s3, v2
	s_mov_b32 s3, 0xa000
	s_nop 0
	v_addc_co_u32_e32 v5, vcc, 0, v3, vcc
	global_load_dwordx4 v[18:21], v[4:5], off
	v_add_co_u32_e32 v4, vcc, s3, v2
	s_mov_b32 s3, 0xc000
	s_nop 0
	v_addc_co_u32_e32 v5, vcc, 0, v3, vcc
	global_load_dwordx4 v[14:17], v[4:5], off
	v_add_co_u32_e32 v4, vcc, s3, v2
	s_mov_b32 s3, 0xe000
	s_nop 0
	v_addc_co_u32_e32 v5, vcc, 0, v3, vcc
	v_add_co_u32_e32 v2, vcc, s3, v2
	global_load_dwordx4 v[10:13], v[4:5], off
	s_nop 0
	v_addc_co_u32_e32 v3, vcc, 0, v3, vcc
	global_load_dwordx4 v[2:5], v[2:3], off
	v_ashrrev_i32_e32 v83, 31, v82
	v_lshlrev_b64 v[82:83], 12, v[82:83]
	v_lshl_add_u64 v[82:83], s[18:19], 0, v[82:83]
	s_lshl_b32 s0, s2, 9
	s_mov_b32 s1, s31
	v_lshl_add_u64 v[114:115], v[82:83], 0, s[0:1]
	v_lshl_add_u64 v[82:83], s[34:35], 1, v[114:115]
	v_lshl_add_u64 v[82:83], v[82:83], 0, v[0:1]
	v_and_b32_e32 v134, 32, v214
	v_lshrrev_b32_e32 v134, 5, v134
	v_mul_u32_u24_e32 v134, 24, v134
	v_sub_u32_e32 v134, 16, v134
	v_ashrrev_i32_e32 v135, 31, v134
	v_lshl_add_u64 v[82:83], v[82:83], 0, v[134:135]
	global_load_dwordx4 v[110:113], v[82:83], off
	global_load_dwordx4 v[106:109], v[82:83], off offset:32
	global_load_dwordx4 v[102:105], v[82:83], off offset:64
	global_load_dwordx4 v[98:101], v[82:83], off offset:96
	global_load_dwordx4 v[94:97], v[82:83], off offset:128
	global_load_dwordx4 v[90:93], v[82:83], off offset:160
	global_load_dwordx4 v[86:89], v[82:83], off offset:192
	s_nop 0
	global_load_dwordx4 v[82:85], v[82:83], off offset:224
	s_waitcnt vmcnt(0)
	v_permlane32_swap_b32_e32 v110, v112
	v_permlane32_swap_b32_e32 v111, v113
	v_permlane32_swap_b32_e32 v106, v108
	v_permlane32_swap_b32_e32 v107, v109
	v_permlane32_swap_b32_e32 v102, v104
	v_permlane32_swap_b32_e32 v103, v105
	v_permlane32_swap_b32_e32 v98, v100
	v_permlane32_swap_b32_e32 v99, v101
	v_permlane32_swap_b32_e32 v94, v96
	v_permlane32_swap_b32_e32 v95, v97
	v_permlane32_swap_b32_e32 v90, v92
	v_permlane32_swap_b32_e32 v91, v93
	v_permlane32_swap_b32_e32 v86, v88
	v_permlane32_swap_b32_e32 v87, v89
	v_permlane32_swap_b32_e32 v82, v84
	v_permlane32_swap_b32_e32 v83, v85
	s_barrier
	ds_write_b128 v118, v[38:41]
	ds_write_b128 v118, v[42:45] offset:8704
	ds_write_b128 v118, v[46:49] offset:17408
	ds_write_b128 v118, v[50:53] offset:26112
	ds_write_b128 v118, v[54:57] offset:34816
	ds_write_b128 v118, v[58:61] offset:43520
	ds_write_b128 v118, v[62:65] offset:52224
	ds_write_b128 v118, v[66:69] offset:60928
	v_mov_b64_e32 v[38:39], s[10:11]
	v_lshl_add_u64 v[52:53], v[80:81], 1, v[114:115]
	v_and_b32_e32 v134, 32, v214
	v_lshrrev_b32_e32 v134, 2, v134
	v_mov_b32_e32 v135, 0
	v_lshl_add_u64 v[52:53], v[52:53], 0, v[134:135]
	s_add_i32 s6, s6, s85
	s_add_i32 s4, s4, s5
	v_pk_fma_f32 v[34:35], v[34:35], s[14:15], v[38:39] op_sel_hi:[1,0,0]
	s_nop 0
	v_mul_f32_e32 v40, 0x4b800000, v34
	v_cmp_gt_f32_e64 s[0:1], s68, v34
	v_cmp_gt_f32_e32 vcc, s68, v35
	v_pk_fma_f32 v[36:37], v[36:37], s[14:15], v[38:39] op_sel_hi:[1,0,0]
	v_cndmask_b32_e64 v34, v34, v40, s[0:1]
	v_mul_f32_e32 v40, 0x4b800000, v35
	v_cndmask_b32_e32 v35, v35, v40, vcc
	v_rsq_f32_e32 v34, v34
	v_rsq_f32_e32 v35, v35
	v_mul_f32_e32 v38, 0x4b800000, v36
	v_pk_mul_f32 v[40:41], v[34:35], s[12:13] op_sel_hi:[1,0]
	s_nop 0
	v_cndmask_b32_e64 v34, v34, v40, s[0:1]
	v_cmp_gt_f32_e64 s[0:1], s68, v36
	v_cndmask_b32_e32 v35, v35, v41, vcc
	v_cmp_gt_f32_e32 vcc, s68, v37
	v_cndmask_b32_e64 v36, v36, v38, s[0:1]
	v_mul_f32_e32 v38, 0x4b800000, v37
	v_cndmask_b32_e32 v37, v37, v38, vcc
	v_rsq_f32_e32 v36, v36
	v_rsq_f32_e32 v37, v37
	v_pk_mul_f32 v[6:7], v[6:7], v[34:35]
	v_pk_mul_f32 v[38:39], v[36:37], s[12:13] op_sel_hi:[1,0]
	s_nop 0
	v_cndmask_b32_e32 v37, v37, v39, vcc
	v_cndmask_b32_e64 v36, v36, v38, s[0:1]
	v_pk_mul_f32 v[8:9], v[8:9], v[36:37]
	v_cvt_pk_bf16_f32 v6, v6, v7
	v_cvt_pk_bf16_f32 v7, v8, v9
	ds_write_b64 v119, v[6:7]
	v_pk_mul_f32 v[6:7], v[32:33], v[36:37]
	v_pk_mul_f32 v[8:9], v[30:31], v[34:35]
	v_and_b32_e32 v69, 0xffff0000, v112
	v_cvt_pk_bf16_f32 v8, v8, v9
	v_cvt_pk_bf16_f32 v9, v6, v7
	ds_write_b64 v119, v[8:9] offset:4352
	v_pk_mul_f32 v[6:7], v[28:29], v[36:37]
	v_pk_mul_f32 v[8:9], v[26:27], v[34:35]
	v_pk_mul_f32 v[4:5], v[4:5], v[36:37]
	v_cvt_pk_bf16_f32 v8, v8, v9
	v_cvt_pk_bf16_f32 v9, v6, v7
	ds_write_b64 v119, v[8:9] offset:8704
	v_pk_mul_f32 v[6:7], v[24:25], v[36:37]
	v_pk_mul_f32 v[8:9], v[22:23], v[34:35]
	v_pk_mul_f32 v[2:3], v[2:3], v[34:35]
	v_cvt_pk_bf16_f32 v8, v8, v9
	v_cvt_pk_bf16_f32 v9, v6, v7
	ds_write_b64 v119, v[8:9] offset:13056
	v_pk_mul_f32 v[6:7], v[20:21], v[36:37]
	v_pk_mul_f32 v[8:9], v[18:19], v[34:35]
	v_cvt_pk_bf16_f32 v2, v2, v3
	v_cvt_pk_bf16_f32 v8, v8, v9
	v_cvt_pk_bf16_f32 v9, v6, v7
	ds_write_b64 v119, v[8:9] offset:17408
	v_pk_mul_f32 v[6:7], v[16:17], v[36:37]
	v_pk_mul_f32 v[8:9], v[14:15], v[34:35]
	v_cvt_pk_bf16_f32 v3, v4, v5
	v_cvt_pk_bf16_f32 v8, v8, v9
	v_cvt_pk_bf16_f32 v9, v6, v7
	ds_write_b64 v119, v[8:9] offset:21760
	v_pk_mul_f32 v[6:7], v[12:13], v[36:37]
	v_pk_mul_f32 v[8:9], v[10:11], v[34:35]
	ds_write_b64 v119, v[2:3] offset:30464
	v_or_b32_e32 v2, s30, v116
	v_cvt_pk_bf16_f32 v8, v8, v9
	v_cvt_pk_bf16_f32 v9, v6, v7
	v_lshlrev_b32_e32 v2, 2, v2
	ds_write_b64 v119, v[8:9] offset:26112
	s_waitcnt lgkmcnt(0)
	s_barrier
	ds_read_b128 v[46:49], v120
	ds_read_b128 v[42:45], v120 offset:32
	ds_read_b128 v[38:41], v120 offset:64
	ds_read_b128 v[34:37], v120 offset:96
	ds_read_b128 v[30:33], v120 offset:128
	ds_read_b128 v[26:29], v120 offset:160
	ds_read_b128 v[22:25], v120 offset:192
	ds_read_b128 v[18:21], v120 offset:224
	global_load_dword v50, v2, s[54:55]
	s_lshl_b32 s30, s2, 10
	v_lshl_add_u64 v[54:55], v[78:79], 0, s[30:31]
	global_load_dwordx4 v[56:59], v[54:55], off
	global_load_dwordx4 v[60:63], v[54:55], off offset:32
	global_load_dwordx4 v[64:67], v[54:55], off offset:64
	global_load_dwordx4 v[122:125], v[54:55], off offset:96
	ds_read_b128 v[2:5], v121
	ds_read_b128 v[126:129], v121 offset:32
	s_waitcnt lgkmcnt(1)
	v_mfma_f32_32x32x16_bf16 v[2:17], v[2:5], v[46:49], 0
	v_lshlrev_b32_e32 v68, 16, v112
	s_cmpk_gt_i32 s6, 0x2ff
	s_waitcnt lgkmcnt(0)
	v_mfma_f32_32x32x16_bf16 v[2:17], v[126:129], v[42:45], v[2:17]
	ds_read_b128 v[126:129], v121 offset:64
	s_waitcnt lgkmcnt(0)
	v_mfma_f32_32x32x16_bf16 v[2:17], v[126:129], v[38:41], v[2:17]
	ds_read_b128 v[126:129], v121 offset:96
	s_waitcnt lgkmcnt(0)
	v_mfma_f32_32x32x16_bf16 v[2:17], v[126:129], v[34:37], v[2:17]
	ds_read_b128 v[126:129], v121 offset:128
	s_waitcnt lgkmcnt(0)
	v_mfma_f32_32x32x16_bf16 v[2:17], v[126:129], v[30:33], v[2:17]
	ds_read_b128 v[126:129], v121 offset:160
	s_waitcnt lgkmcnt(0)
	v_mfma_f32_32x32x16_bf16 v[2:17], v[126:129], v[26:29], v[2:17]
	ds_read_b128 v[126:129], v121 offset:192
	s_waitcnt lgkmcnt(0)
	v_mfma_f32_32x32x16_bf16 v[2:17], v[126:129], v[22:25], v[2:17]
	ds_read_b128 v[126:129], v121 offset:224
	s_waitcnt lgkmcnt(0)
	v_mfma_f32_32x32x16_bf16 v[2:17], v[126:129], v[18:21], v[2:17]
	s_waitcnt vmcnt(3)
	s_nop 10
	v_pk_fma_f32 v[2:3], v[56:57], v[2:3], v[50:51] op_sel_hi:[1,1,0]
	v_and_b32_e32 v57, 0xffff0000, v113
	v_lshlrev_b32_e32 v56, 16, v113
	v_pk_fma_f32 v[4:5], v[58:59], v[4:5], v[50:51] op_sel_hi:[1,1,0]
	v_pk_mul_f32 v[2:3], v[2:3], v[68:69]
	v_pk_mul_f32 v[4:5], v[4:5], v[56:57]
	v_cvt_pk_bf16_f32 v130, v2, v3
	v_cvt_pk_bf16_f32 v131, v4, v5
	v_and_b32_e32 v3, 0xffff0000, v110
	v_lshlrev_b32_e32 v2, 16, v110
	s_waitcnt vmcnt(2)
	v_pk_fma_f32 v[4:5], v[60:61], v[6:7], v[50:51] op_sel_hi:[1,1,0]
	v_pk_fma_f32 v[6:7], v[62:63], v[8:9], v[50:51] op_sel_hi:[1,1,0]
	v_pk_mul_f32 v[2:3], v[4:5], v[2:3]
	v_and_b32_e32 v5, 0xffff0000, v111
	v_lshlrev_b32_e32 v4, 16, v111
	v_pk_mul_f32 v[4:5], v[6:7], v[4:5]
	v_cvt_pk_bf16_f32 v132, v2, v3
	v_cvt_pk_bf16_f32 v133, v4, v5
	s_nop 1
	v_permlane32_swap_b32_e32 v130, v132
	v_permlane32_swap_b32_e32 v131, v133
	global_store_dwordx4 v[52:53], v[130:133], off
	v_and_b32_e32 v3, 0xffff0000, v108
	v_lshlrev_b32_e32 v2, 16, v108
	s_waitcnt vmcnt(2)
	v_pk_fma_f32 v[4:5], v[64:65], v[10:11], v[50:51] op_sel_hi:[1,1,0]
	v_pk_fma_f32 v[6:7], v[66:67], v[12:13], v[50:51] op_sel_hi:[1,1,0]
	v_pk_mul_f32 v[2:3], v[4:5], v[2:3]
	v_and_b32_e32 v5, 0xffff0000, v109
	v_lshlrev_b32_e32 v4, 16, v109
	v_pk_mul_f32 v[4:5], v[6:7], v[4:5]
	v_cvt_pk_bf16_f32 v130, v2, v3
	v_cvt_pk_bf16_f32 v131, v4, v5
	v_and_b32_e32 v3, 0xffff0000, v106
	v_lshlrev_b32_e32 v2, 16, v106
	s_waitcnt vmcnt(1)
	v_pk_fma_f32 v[4:5], v[122:123], v[14:15], v[50:51] op_sel_hi:[1,1,0]
	v_pk_fma_f32 v[6:7], v[124:125], v[16:17], v[50:51] op_sel_hi:[1,1,0]
	v_pk_mul_f32 v[2:3], v[4:5], v[2:3]
	v_and_b32_e32 v5, 0xffff0000, v107
	v_lshlrev_b32_e32 v4, 16, v107
	v_pk_mul_f32 v[4:5], v[6:7], v[4:5]
	v_cvt_pk_bf16_f32 v132, v2, v3
	v_cvt_pk_bf16_f32 v133, v4, v5
	s_nop 1
	v_permlane32_swap_b32_e32 v130, v132
	v_permlane32_swap_b32_e32 v131, v133
	global_store_dwordx4 v[52:53], v[130:133], off offset:32
	global_load_dwordx4 v[56:59], v[54:55], off offset:128
	global_load_dwordx4 v[60:63], v[54:55], off offset:160
	global_load_dwordx4 v[64:67], v[54:55], off offset:192
	global_load_dwordx4 v[106:109], v[54:55], off offset:224
	ds_read_b128 v[2:5], v121 offset:8704
	ds_read_b128 v[110:113], v121 offset:8736
	s_waitcnt lgkmcnt(1)
	v_mfma_f32_32x32x16_bf16 v[2:17], v[2:5], v[46:49], 0
	v_and_b32_e32 v69, 0xffff0000, v104
	v_lshlrev_b32_e32 v68, 16, v104
	s_waitcnt lgkmcnt(0)
	v_mfma_f32_32x32x16_bf16 v[2:17], v[110:113], v[42:45], v[2:17]
	ds_read_b128 v[110:113], v121 offset:8768
	s_waitcnt lgkmcnt(0)
	v_mfma_f32_32x32x16_bf16 v[2:17], v[110:113], v[38:41], v[2:17]
	ds_read_b128 v[110:113], v121 offset:8800
	s_waitcnt lgkmcnt(0)
	v_mfma_f32_32x32x16_bf16 v[2:17], v[110:113], v[34:37], v[2:17]
	ds_read_b128 v[110:113], v121 offset:8832
	s_waitcnt lgkmcnt(0)
	v_mfma_f32_32x32x16_bf16 v[2:17], v[110:113], v[30:33], v[2:17]
	ds_read_b128 v[110:113], v121 offset:8864
	s_waitcnt lgkmcnt(0)
	v_mfma_f32_32x32x16_bf16 v[2:17], v[110:113], v[26:29], v[2:17]
	ds_read_b128 v[110:113], v121 offset:8896
	s_waitcnt lgkmcnt(0)
	v_mfma_f32_32x32x16_bf16 v[2:17], v[110:113], v[22:25], v[2:17]
	ds_read_b128 v[110:113], v121 offset:8928
	s_waitcnt lgkmcnt(0)
	v_mfma_f32_32x32x16_bf16 v[2:17], v[110:113], v[18:21], v[2:17]
	s_waitcnt vmcnt(3)
	s_nop 10
	v_pk_fma_f32 v[2:3], v[56:57], v[2:3], v[50:51] op_sel_hi:[1,1,0]
	v_and_b32_e32 v57, 0xffff0000, v105
	v_lshlrev_b32_e32 v56, 16, v105
	v_pk_fma_f32 v[4:5], v[58:59], v[4:5], v[50:51] op_sel_hi:[1,1,0]
	v_pk_mul_f32 v[2:3], v[2:3], v[68:69]
	v_pk_mul_f32 v[4:5], v[4:5], v[56:57]
	v_cvt_pk_bf16_f32 v130, v2, v3
	v_cvt_pk_bf16_f32 v131, v4, v5
	v_and_b32_e32 v3, 0xffff0000, v102
	v_lshlrev_b32_e32 v2, 16, v102
	s_waitcnt vmcnt(2)
	v_pk_fma_f32 v[4:5], v[60:61], v[6:7], v[50:51] op_sel_hi:[1,1,0]
	v_pk_fma_f32 v[6:7], v[62:63], v[8:9], v[50:51] op_sel_hi:[1,1,0]
	v_pk_mul_f32 v[2:3], v[4:5], v[2:3]
	v_and_b32_e32 v5, 0xffff0000, v103
	v_lshlrev_b32_e32 v4, 16, v103
	v_pk_mul_f32 v[4:5], v[6:7], v[4:5]
	v_cvt_pk_bf16_f32 v132, v2, v3
	v_cvt_pk_bf16_f32 v133, v4, v5
	s_nop 1
	v_permlane32_swap_b32_e32 v130, v132
	v_permlane32_swap_b32_e32 v131, v133
	global_store_dwordx4 v[52:53], v[130:133], off offset:64
	v_and_b32_e32 v3, 0xffff0000, v100
	v_lshlrev_b32_e32 v2, 16, v100
	s_waitcnt vmcnt(2)
	v_pk_fma_f32 v[4:5], v[64:65], v[10:11], v[50:51] op_sel_hi:[1,1,0]
	v_pk_fma_f32 v[6:7], v[66:67], v[12:13], v[50:51] op_sel_hi:[1,1,0]
	v_pk_mul_f32 v[2:3], v[4:5], v[2:3]
	v_and_b32_e32 v5, 0xffff0000, v101
	v_lshlrev_b32_e32 v4, 16, v101
	v_pk_mul_f32 v[4:5], v[6:7], v[4:5]
	v_cvt_pk_bf16_f32 v130, v2, v3
	v_cvt_pk_bf16_f32 v131, v4, v5
	v_and_b32_e32 v3, 0xffff0000, v98
	v_lshlrev_b32_e32 v2, 16, v98
	s_waitcnt vmcnt(1)
	v_pk_fma_f32 v[4:5], v[106:107], v[14:15], v[50:51] op_sel_hi:[1,1,0]
	v_pk_fma_f32 v[6:7], v[108:109], v[16:17], v[50:51] op_sel_hi:[1,1,0]
	v_pk_mul_f32 v[2:3], v[4:5], v[2:3]
	v_and_b32_e32 v5, 0xffff0000, v99
	v_lshlrev_b32_e32 v4, 16, v99
	v_pk_mul_f32 v[4:5], v[6:7], v[4:5]
	v_cvt_pk_bf16_f32 v132, v2, v3
	v_cvt_pk_bf16_f32 v133, v4, v5
	s_nop 1
	v_permlane32_swap_b32_e32 v130, v132
	v_permlane32_swap_b32_e32 v131, v133
	global_store_dwordx4 v[52:53], v[130:133], off offset:96
	global_load_dwordx4 v[56:59], v[54:55], off offset:256
	global_load_dwordx4 v[60:63], v[54:55], off offset:288
	global_load_dwordx4 v[64:67], v[54:55], off offset:320
	global_load_dwordx4 v[98:101], v[54:55], off offset:352
	ds_read_b128 v[2:5], v121 offset:17408
	ds_read_b128 v[102:105], v121 offset:17440
	s_waitcnt lgkmcnt(1)
	v_mfma_f32_32x32x16_bf16 v[2:17], v[2:5], v[46:49], 0
	v_and_b32_e32 v69, 0xffff0000, v96
	v_lshlrev_b32_e32 v68, 16, v96
	s_waitcnt lgkmcnt(0)
	v_mfma_f32_32x32x16_bf16 v[2:17], v[102:105], v[42:45], v[2:17]
	ds_read_b128 v[102:105], v121 offset:17472
	s_waitcnt lgkmcnt(0)
	v_mfma_f32_32x32x16_bf16 v[2:17], v[102:105], v[38:41], v[2:17]
	ds_read_b128 v[102:105], v121 offset:17504
	s_waitcnt lgkmcnt(0)
	v_mfma_f32_32x32x16_bf16 v[2:17], v[102:105], v[34:37], v[2:17]
	ds_read_b128 v[102:105], v121 offset:17536
	s_waitcnt lgkmcnt(0)
	v_mfma_f32_32x32x16_bf16 v[2:17], v[102:105], v[30:33], v[2:17]
	ds_read_b128 v[102:105], v121 offset:17568
	s_waitcnt lgkmcnt(0)
	v_mfma_f32_32x32x16_bf16 v[2:17], v[102:105], v[26:29], v[2:17]
	ds_read_b128 v[102:105], v121 offset:17600
	s_waitcnt lgkmcnt(0)
	v_mfma_f32_32x32x16_bf16 v[2:17], v[102:105], v[22:25], v[2:17]
	ds_read_b128 v[102:105], v121 offset:17632
	s_waitcnt lgkmcnt(0)
	v_mfma_f32_32x32x16_bf16 v[2:17], v[102:105], v[18:21], v[2:17]
	s_waitcnt vmcnt(3)
	s_nop 10
	v_pk_fma_f32 v[2:3], v[56:57], v[2:3], v[50:51] op_sel_hi:[1,1,0]
	v_and_b32_e32 v57, 0xffff0000, v97
	v_lshlrev_b32_e32 v56, 16, v97
	v_pk_fma_f32 v[4:5], v[58:59], v[4:5], v[50:51] op_sel_hi:[1,1,0]
	v_pk_mul_f32 v[2:3], v[2:3], v[68:69]
	v_pk_mul_f32 v[4:5], v[4:5], v[56:57]
	v_cvt_pk_bf16_f32 v130, v2, v3
	v_cvt_pk_bf16_f32 v131, v4, v5
	v_and_b32_e32 v3, 0xffff0000, v94
	v_lshlrev_b32_e32 v2, 16, v94
	s_waitcnt vmcnt(2)
	v_pk_fma_f32 v[4:5], v[60:61], v[6:7], v[50:51] op_sel_hi:[1,1,0]
	v_pk_fma_f32 v[6:7], v[62:63], v[8:9], v[50:51] op_sel_hi:[1,1,0]
	v_pk_mul_f32 v[2:3], v[4:5], v[2:3]
	v_and_b32_e32 v5, 0xffff0000, v95
	v_lshlrev_b32_e32 v4, 16, v95
	v_pk_mul_f32 v[4:5], v[6:7], v[4:5]
	v_cvt_pk_bf16_f32 v132, v2, v3
	v_cvt_pk_bf16_f32 v133, v4, v5
	s_nop 1
	v_permlane32_swap_b32_e32 v130, v132
	v_permlane32_swap_b32_e32 v131, v133
	global_store_dwordx4 v[52:53], v[130:133], off offset:128
	v_and_b32_e32 v3, 0xffff0000, v92
	v_lshlrev_b32_e32 v2, 16, v92
	s_waitcnt vmcnt(2)
	v_pk_fma_f32 v[4:5], v[64:65], v[10:11], v[50:51] op_sel_hi:[1,1,0]
	v_pk_fma_f32 v[6:7], v[66:67], v[12:13], v[50:51] op_sel_hi:[1,1,0]
	v_pk_mul_f32 v[2:3], v[4:5], v[2:3]
	v_and_b32_e32 v5, 0xffff0000, v93
	v_lshlrev_b32_e32 v4, 16, v93
	v_pk_mul_f32 v[4:5], v[6:7], v[4:5]
	v_cvt_pk_bf16_f32 v130, v2, v3
	v_cvt_pk_bf16_f32 v131, v4, v5
	v_and_b32_e32 v3, 0xffff0000, v90
	v_lshlrev_b32_e32 v2, 16, v90
	s_waitcnt vmcnt(1)
	v_pk_fma_f32 v[4:5], v[98:99], v[14:15], v[50:51] op_sel_hi:[1,1,0]
	v_pk_fma_f32 v[6:7], v[100:101], v[16:17], v[50:51] op_sel_hi:[1,1,0]
	v_pk_mul_f32 v[2:3], v[4:5], v[2:3]
	v_and_b32_e32 v5, 0xffff0000, v91
	v_lshlrev_b32_e32 v4, 16, v91
	v_pk_mul_f32 v[4:5], v[6:7], v[4:5]
	v_cvt_pk_bf16_f32 v132, v2, v3
	v_cvt_pk_bf16_f32 v133, v4, v5
	s_nop 1
	v_permlane32_swap_b32_e32 v130, v132
	v_permlane32_swap_b32_e32 v131, v133
	global_store_dwordx4 v[52:53], v[130:133], off offset:160
	global_load_dwordx4 v[56:59], v[54:55], off offset:384
	global_load_dwordx4 v[60:63], v[54:55], off offset:416
	global_load_dwordx4 v[64:67], v[54:55], off offset:448
	global_load_dwordx4 v[90:93], v[54:55], off offset:480
	ds_read_b128 v[2:5], v121 offset:26112
	ds_read_b128 v[94:97], v121 offset:26144
	s_waitcnt lgkmcnt(1)
	v_mfma_f32_32x32x16_bf16 v[2:17], v[2:5], v[46:49], 0
	s_waitcnt lgkmcnt(0)
	v_mfma_f32_32x32x16_bf16 v[2:17], v[94:97], v[42:45], v[2:17]
	ds_read_b128 v[42:45], v121 offset:26176
	s_waitcnt lgkmcnt(0)
	v_mfma_f32_32x32x16_bf16 v[2:17], v[42:45], v[38:41], v[2:17]
	ds_read_b128 v[38:41], v121 offset:26208
	s_waitcnt lgkmcnt(0)
	v_mfma_f32_32x32x16_bf16 v[2:17], v[38:41], v[34:37], v[2:17]
	ds_read_b128 v[34:37], v121 offset:26240
	s_waitcnt lgkmcnt(0)
	v_mfma_f32_32x32x16_bf16 v[2:17], v[34:37], v[30:33], v[2:17]
	ds_read_b128 v[30:33], v121 offset:26272
	s_waitcnt lgkmcnt(0)
	v_mfma_f32_32x32x16_bf16 v[2:17], v[30:33], v[26:29], v[2:17]
	ds_read_b128 v[26:29], v121 offset:26304
	s_waitcnt lgkmcnt(0)
	v_mfma_f32_32x32x16_bf16 v[2:17], v[26:29], v[22:25], v[2:17]
	ds_read_b128 v[22:25], v121 offset:26336
	s_waitcnt lgkmcnt(0)
	v_mfma_f32_32x32x16_bf16 v[2:17], v[22:25], v[18:21], v[2:17]
	v_and_b32_e32 v19, 0xffff0000, v88
	v_lshlrev_b32_e32 v18, 16, v88
	s_waitcnt vmcnt(3)
	s_nop 8
	v_pk_fma_f32 v[2:3], v[56:57], v[2:3], v[50:51] op_sel_hi:[1,1,0]
	v_pk_fma_f32 v[4:5], v[58:59], v[4:5], v[50:51] op_sel_hi:[1,1,0]
	v_pk_mul_f32 v[2:3], v[2:3], v[18:19]
	v_and_b32_e32 v19, 0xffff0000, v89
	v_lshlrev_b32_e32 v18, 16, v89
	v_pk_mul_f32 v[4:5], v[4:5], v[18:19]
	v_cvt_pk_bf16_f32 v130, v2, v3
	v_cvt_pk_bf16_f32 v131, v4, v5
	v_and_b32_e32 v3, 0xffff0000, v86
	v_lshlrev_b32_e32 v2, 16, v86
	s_waitcnt vmcnt(2)
	v_pk_fma_f32 v[4:5], v[60:61], v[6:7], v[50:51] op_sel_hi:[1,1,0]
	v_pk_fma_f32 v[6:7], v[62:63], v[8:9], v[50:51] op_sel_hi:[1,1,0]
	v_pk_mul_f32 v[2:3], v[4:5], v[2:3]
	v_and_b32_e32 v5, 0xffff0000, v87
	v_lshlrev_b32_e32 v4, 16, v87
	v_pk_mul_f32 v[4:5], v[6:7], v[4:5]
	v_cvt_pk_bf16_f32 v132, v2, v3
	v_cvt_pk_bf16_f32 v133, v4, v5
	s_nop 1
	v_permlane32_swap_b32_e32 v130, v132
	v_permlane32_swap_b32_e32 v131, v133
	global_store_dwordx4 v[52:53], v[130:133], off offset:192
	v_and_b32_e32 v3, 0xffff0000, v84
	v_lshlrev_b32_e32 v2, 16, v84
	s_waitcnt vmcnt(2)
	v_pk_fma_f32 v[4:5], v[64:65], v[10:11], v[50:51] op_sel_hi:[1,1,0]
	v_pk_fma_f32 v[6:7], v[66:67], v[12:13], v[50:51] op_sel_hi:[1,1,0]
	v_pk_mul_f32 v[2:3], v[4:5], v[2:3]
	v_and_b32_e32 v5, 0xffff0000, v85
	v_lshlrev_b32_e32 v4, 16, v85
	v_pk_mul_f32 v[4:5], v[6:7], v[4:5]
	v_cvt_pk_bf16_f32 v130, v2, v3
	v_cvt_pk_bf16_f32 v131, v4, v5
	v_and_b32_e32 v3, 0xffff0000, v82
	v_lshlrev_b32_e32 v2, 16, v82
	s_waitcnt vmcnt(1)
	v_pk_fma_f32 v[4:5], v[90:91], v[14:15], v[50:51] op_sel_hi:[1,1,0]
	v_pk_fma_f32 v[6:7], v[92:93], v[16:17], v[50:51] op_sel_hi:[1,1,0]
	v_pk_mul_f32 v[2:3], v[4:5], v[2:3]
	v_and_b32_e32 v5, 0xffff0000, v83
	v_lshlrev_b32_e32 v4, 16, v83
	v_pk_mul_f32 v[4:5], v[6:7], v[4:5]
	v_cvt_pk_bf16_f32 v132, v2, v3
	v_cvt_pk_bf16_f32 v133, v4, v5
	s_nop 1
	v_permlane32_swap_b32_e32 v130, v132
	v_permlane32_swap_b32_e32 v131, v133
	global_store_dwordx4 v[52:53], v[130:133], off offset:224
	s_cbranch_scc0 .LBB0_675

.LBB0_716:
	s_cmp_lt_u32 s41, 8
	s_cselect_b64 s[22:23], -1, 0
	s_or_b64 s[22:23], s[4:5], s[22:23]
	s_add_i32 s27, s29, s41
	s_cmp_ge_i32 s27, s28
	s_cselect_b64 s[42:43], -1, 0
	s_cmp_lt_i32 s27, s33
	s_cselect_b64 s[74:75], -1, 0
	s_and_b64 s[42:43], s[42:43], s[74:75]
	s_or_b64 s[42:43], s[22:23], s[42:43]
	s_andn2_b64 vcc, exec, s[42:43]
	s_cbranch_vccnz .LBB0_798
	s_add_i32 s27, s26, 0x780
	s_and_b32 s27, s27, 64
	s_mulk_i32 s27, 0x90
	v_add_u32_e32 v0, s27, v106
	ds_read_b128 v[34:37], v0
	ds_read_b128 v[140:143], v0 offset:4640
	s_xor_b64 s[22:23], s[22:23], -1
	s_andn2_b64 vcc, exec, s[22:23]
	s_waitcnt lgkmcnt(1)
	v_mfma_f32_32x32x16_bf16 v[50:65], v[34:37], v[66:69], 0
	ds_read_b128 v[34:37], v0 offset:32
	s_waitcnt lgkmcnt(0)
	v_mfma_f32_32x32x16_bf16 v[50:65], v[34:37], v[70:73], v[50:65]
	ds_read_b128 v[34:37], v0 offset:64
	s_waitcnt lgkmcnt(0)
	v_mfma_f32_32x32x16_bf16 v[50:65], v[34:37], v[74:77], v[50:65]
	ds_read_b128 v[34:37], v0 offset:96
	s_waitcnt lgkmcnt(0)
	v_mfma_f32_32x32x16_bf16 v[50:65], v[34:37], v[78:81], v[50:65]
	ds_read_b128 v[34:37], v0 offset:4608
	s_waitcnt lgkmcnt(0)
	v_mfma_f32_32x32x16_bf16 v[34:49], v[34:37], v[66:69], 0
	v_mfma_f32_32x32x16_bf16 v[34:49], v[140:143], v[70:73], v[34:49]
	ds_read_b128 v[140:143], v0 offset:4672
	s_waitcnt lgkmcnt(0)
	v_mfma_f32_32x32x16_bf16 v[34:49], v[140:143], v[74:77], v[34:49]
	ds_read_b128 v[140:143], v0 offset:4704
	s_waitcnt lgkmcnt(0)
	v_mfma_f32_32x32x16_bf16 v[34:49], v[140:143], v[78:81], v[34:49]
	s_cbranch_vccnz .LBB0_794
	ds_read_b32 v216, v99
	ds_read_b32 v217, v99 offset:4
	ds_read_b32 v218, v99 offset:8
	ds_read_b32 v219, v99 offset:12
	ds_read_b32 v220, v99 offset:32
	ds_read_b32 v221, v99 offset:36
	ds_read_b32 v222, v99 offset:40
	ds_read_b32 v223, v99 offset:44
	ds_read_b32 v224, v99 offset:64
	ds_read_b32 v225, v99 offset:68
	ds_read_b32 v226, v99 offset:72
	ds_read_b32 v227, v99 offset:76
	ds_read_b32 v228, v99 offset:96
	ds_read_b32 v229, v99 offset:100
	ds_read_b32 v230, v99 offset:104
	ds_read_b32 v231, v99 offset:108
	ds_read_b32 v232, v99 offset:128
	ds_read_b32 v233, v99 offset:132
	ds_read_b32 v234, v99 offset:136
	ds_read_b32 v235, v99 offset:140
	ds_read_b32 v236, v99 offset:160
	ds_read_b32 v237, v99 offset:164
	ds_read_b32 v238, v99 offset:168
	ds_read_b32 v239, v99 offset:172
	ds_read_b32 v240, v99 offset:192
	ds_read_b32 v241, v99 offset:196
	ds_read_b32 v242, v99 offset:200
	ds_read_b32 v243, v99 offset:204
	ds_read_b32 v244, v99 offset:224
	ds_read_b32 v245, v99 offset:228
	ds_read_b32 v246, v99 offset:232
	ds_read_b32 v247, v99 offset:236
	s_waitcnt lgkmcnt(0)
	v_mov_b32_e32 v139, 0xf149f2ca
	v_mov_b32_e32 v140, 0xf149f2ca
	s_mov_b64 s[22:23], exec
	v_readlane_b32 s42, v255, 0
	v_readlane_b32 s43, v255, 1
	s_and_b64 s[42:43], s[22:23], s[42:43]
	s_mov_b64 exec, s[42:43]
	s_cbranch_execz .LBB0_720
	v_add_f32_e32 v140, v50, v216
.LBB0_720:
	s_or_b64 exec, exec, s[22:23]
	s_mov_b64 s[22:23], exec
	v_readlane_b32 s42, v255, 2
	v_readlane_b32 s43, v255, 3
	s_and_b64 s[42:43], s[22:23], s[42:43]
	s_mov_b64 exec, s[42:43]
	s_cbranch_execz .LBB0_722
	v_add_f32_e32 v139, v51, v217
.LBB0_722:
	s_or_b64 exec, exec, s[22:23]
	v_mov_b32_e32 v141, 0xf149f2ca
	v_mov_b32_e32 v143, 0xf149f2ca
	s_and_saveexec_b64 s[22:23], s[44:45]
	s_cbranch_execz .LBB0_724
	v_add_f32_e32 v143, v52, v218
.LBB0_724:
	s_or_b64 exec, exec, s[22:23]
	s_and_saveexec_b64 s[22:23], s[46:47]
	s_cbranch_execz .LBB0_726
	v_add_f32_e32 v141, v53, v219
.LBB0_726:
	s_or_b64 exec, exec, s[22:23]
	v_mov_b32_e32 v142, 0xf149f2ca
	v_mov_b32_e32 v144, 0xf149f2ca
	s_and_saveexec_b64 s[22:23], s[48:49]
	s_cbranch_execz .LBB0_728
	v_add_f32_e32 v144, v54, v220
.LBB0_728:
	s_or_b64 exec, exec, s[22:23]
	s_and_saveexec_b64 s[22:23], s[50:51]
	s_cbranch_execz .LBB0_730
	v_add_f32_e32 v142, v55, v221
.LBB0_730:
	s_or_b64 exec, exec, s[22:23]
	v_mov_b32_e32 v146, 0xf149f2ca
	v_mov_b32_e32 v147, 0xf149f2ca
	s_and_saveexec_b64 s[22:23], s[52:53]
	s_cbranch_execz .LBB0_732
	v_add_f32_e32 v147, v56, v222
.LBB0_732:
	s_or_b64 exec, exec, s[22:23]
	s_and_saveexec_b64 s[22:23], s[54:55]
	s_cbranch_execz .LBB0_734
	v_add_f32_e32 v146, v57, v223
.LBB0_734:
	s_or_b64 exec, exec, s[22:23]
	v_mov_b32_e32 v148, 0xf149f2ca
	v_mov_b32_e32 v150, 0xf149f2ca
	s_and_saveexec_b64 s[22:23], s[10:11]
	s_cbranch_execz .LBB0_736
	v_add_f32_e32 v150, v58, v224
.LBB0_736:
	s_or_b64 exec, exec, s[22:23]
	s_and_saveexec_b64 s[22:23], s[12:13]
	s_cbranch_execz .LBB0_738
	v_add_f32_e32 v148, v59, v225
.LBB0_738:
	s_or_b64 exec, exec, s[22:23]
	v_mov_b32_e32 v151, 0xf149f2ca
	v_mov_b32_e32 v152, 0xf149f2ca
	s_and_saveexec_b64 s[22:23], s[14:15]
	s_cbranch_execz .LBB0_740
	v_add_f32_e32 v152, v60, v226
.LBB0_740:
	s_or_b64 exec, exec, s[22:23]
	s_and_saveexec_b64 s[22:23], s[16:17]
	s_cbranch_execz .LBB0_742
	v_add_f32_e32 v151, v61, v227
.LBB0_742:
	s_or_b64 exec, exec, s[22:23]
	v_mov_b32_e32 v153, 0xf149f2ca
	v_mov_b32_e32 v154, 0xf149f2ca
	s_and_saveexec_b64 s[22:23], s[18:19]
	s_cbranch_execz .LBB0_744
	v_add_f32_e32 v154, v62, v228
.LBB0_744:
	s_or_b64 exec, exec, s[22:23]
	s_and_saveexec_b64 s[22:23], s[72:73]
	s_cbranch_execz .LBB0_746
	v_add_f32_e32 v153, v63, v229
.LBB0_746:
	s_or_b64 exec, exec, s[22:23]
	v_mov_b32_e32 v145, 0xf149f2ca
	v_mov_b32_e32 v149, 0xf149f2ca
	s_and_saveexec_b64 s[22:23], s[76:77]
	s_cbranch_execz .LBB0_748
	v_add_f32_e32 v149, v64, v230
.LBB0_748:
	s_or_b64 exec, exec, s[22:23]
	s_and_saveexec_b64 s[22:23], s[78:79]
	s_cbranch_execz .LBB0_750
	v_add_f32_e32 v145, v65, v231
.LBB0_750:
	s_or_b64 exec, exec, s[22:23]
	v_mov_b32_e32 v162, 0xf149f2ca
	v_mov_b32_e32 v164, 0xf149f2ca
	s_and_saveexec_b64 s[22:23], s[80:81]
	s_cbranch_execz .LBB0_752
	v_add_f32_e32 v164, v34, v232
.LBB0_752:
	s_or_b64 exec, exec, s[22:23]
	s_and_saveexec_b64 s[22:23], s[82:83]
	s_cbranch_execz .LBB0_754
	v_add_f32_e32 v162, v35, v233
.LBB0_754:
	s_or_b64 exec, exec, s[22:23]
	v_mov_b32_e32 v165, 0xf149f2ca
	v_mov_b32_e32 v167, 0xf149f2ca
	s_and_saveexec_b64 s[22:23], s[84:85]
	s_cbranch_execz .LBB0_756
	v_add_f32_e32 v167, v36, v234
.LBB0_756:
	s_or_b64 exec, exec, s[22:23]
	s_and_saveexec_b64 s[22:23], s[86:87]
	s_cbranch_execz .LBB0_758
	v_add_f32_e32 v165, v37, v235
.LBB0_758:
	s_or_b64 exec, exec, s[22:23]
	v_mov_b32_e32 v166, 0xf149f2ca
	v_mov_b32_e32 v168, 0xf149f2ca
	s_and_saveexec_b64 s[22:23], s[88:89]
	s_cbranch_execz .LBB0_760
	v_add_f32_e32 v168, v38, v236
.LBB0_760:
	s_or_b64 exec, exec, s[22:23]
	s_and_saveexec_b64 s[22:23], s[90:91]
	s_cbranch_execz .LBB0_762
	v_add_f32_e32 v166, v39, v237
.LBB0_762:
	s_or_b64 exec, exec, s[22:23]
	v_mov_b32_e32 v169, 0xf149f2ca
	v_mov_b32_e32 v170, 0xf149f2ca
	s_and_saveexec_b64 s[22:23], s[20:21]
	s_cbranch_execz .LBB0_764
	v_add_f32_e32 v170, v40, v238
.LBB0_764:
	s_or_b64 exec, exec, s[22:23]
	s_and_saveexec_b64 s[22:23], s[0:1]
	s_cbranch_execz .LBB0_766
	v_add_f32_e32 v169, v41, v239
.LBB0_766:
	s_or_b64 exec, exec, s[22:23]
	v_mov_b32_e32 v155, 0xf149f2ca
	v_mov_b32_e32 v156, 0xf149f2ca
	s_and_saveexec_b64 s[22:23], s[56:57]
	s_cbranch_execz .LBB0_768
	v_add_f32_e32 v156, v42, v240
.LBB0_768:
	s_or_b64 exec, exec, s[22:23]
	s_and_saveexec_b64 s[22:23], s[58:59]
	s_cbranch_execz .LBB0_770
	v_add_f32_e32 v155, v43, v241
.LBB0_770:
	s_or_b64 exec, exec, s[22:23]
	v_mov_b32_e32 v157, 0xf149f2ca
	v_mov_b32_e32 v158, 0xf149f2ca
	s_and_saveexec_b64 s[22:23], s[60:61]
	s_cbranch_execz .LBB0_772
	v_add_f32_e32 v158, v44, v242
.LBB0_772:
	s_or_b64 exec, exec, s[22:23]
	s_and_saveexec_b64 s[22:23], s[62:63]
	s_cbranch_execz .LBB0_774
	v_add_f32_e32 v157, v45, v243
.LBB0_774:
	s_or_b64 exec, exec, s[22:23]
	v_mov_b32_e32 v160, 0xf149f2ca
	v_mov_b32_e32 v161, 0xf149f2ca
	s_and_saveexec_b64 s[22:23], s[64:65]
	s_cbranch_execz .LBB0_776
	v_add_f32_e32 v161, v46, v244
.LBB0_776:
	s_or_b64 exec, exec, s[22:23]
	s_and_saveexec_b64 s[22:23], s[66:67]
	s_cbranch_execz .LBB0_778
	v_add_f32_e32 v160, v47, v245
.LBB0_778:
	s_or_b64 exec, exec, s[22:23]
	v_mov_b32_e32 v159, 0xf149f2ca
	v_mov_b32_e32 v163, 0xf149f2ca
	s_and_saveexec_b64 s[22:23], s[68:69]
	s_cbranch_execz .LBB0_780
	v_add_f32_e32 v163, v48, v246
.LBB0_780:
	s_or_b64 exec, exec, s[22:23]
	s_and_saveexec_b64 s[22:23], s[70:71]
	s_cbranch_execz .LBB0_782
	v_add_f32_e32 v159, v49, v247

.LBB0_794:
	s_nop 10
	v_pk_mov_b32 v[140:141], v[50:51], v[52:53] op_sel:[0,1]
	v_pk_mov_b32 v[142:143], v[54:55], v[52:53] op_sel:[1,0]
	v_pk_mov_b32 v[144:145], v[54:55], v[64:65] op_sel:[0,1]
	v_pk_mov_b32 v[146:147], v[56:57], v[56:57] op_sel:[1,0]
	v_pk_mov_b32 v[148:149], v[58:59], v[64:65] op_sel:[1,0]
	v_pk_mov_b32 v[150:151], v[58:59], v[60:61] op_sel:[0,1]
	v_pk_mov_b32 v[152:153], v[60:61], v[62:63] op_sel:[0,1]
	v_pk_mov_b32 v[154:155], v[62:63], v[42:43] op_sel:[0,1]
	v_pk_mov_b32 v[156:157], v[42:43], v[44:45] op_sel:[0,1]
	v_pk_mov_b32 v[158:159], v[44:45], v[48:49] op_sel:[0,1]
	v_pk_mov_b32 v[160:161], v[46:47], v[46:47] op_sel:[1,0]
	v_pk_mov_b32 v[162:163], v[34:35], v[48:49] op_sel:[1,0]
	v_pk_mov_b32 v[164:165], v[34:35], v[36:37] op_sel:[0,1]
	v_pk_mov_b32 v[166:167], v[38:39], v[36:37] op_sel:[1,0]
	v_pk_mov_b32 v[168:169], v[38:39], v[40:41] op_sel:[0,1]
	v_mov_b32_e32 v139, v51
	v_mov_b32_e32 v170, v40
.LBB0_795:
	v_max3_f32 v34, v139, v140, v141
	v_max3_f32 v35, v142, v143, v144
	v_max3_f32 v36, v145, v146, v147
	v_max3_f32 v37, v148, v149, v150
	v_max3_f32 v34, v34, v151, v152
	v_max3_f32 v35, v35, v153, v154
	v_max3_f32 v36, v36, v155, v156
	v_max3_f32 v37, v37, v157, v158
	v_max3_f32 v34, v34, v159, v160
	v_max3_f32 v35, v35, v161, v162
	v_max3_f32 v36, v36, v163, v164
	v_max3_f32 v37, v37, v165, v166
	v_max3_f32 v34, v34, v167, v168
	v_max3_f32 v35, v35, v169, v170
	v_max3_f32 v34, v34, v35, v36
	v_max_f32_e32 v34, v34, v37
	v_mov_b32_e32 v35, v34
	s_nop 1
	v_permlane32_swap_b32_e32 v34, v35
	v_max_f32_e32 v35, v35, v35
	v_max_f32_e32 v34, v34, v34
	v_max_f32_e32 v34, v34, v35
	v_cmp_gt_f32_e32 vcc, v34, v101
	s_cbranch_vccz .LBB0_797
	v_max_f32_e32 v34, v34, v34
	v_max_f32_e32 v35, v101, v101
	v_max_f32_e32 v35, v35, v34
	v_sub_f32_e32 v34, v101, v35
	v_exp_f32_e32 v34, v34
	v_mov_b32_e32 v101, v35
	v_pk_mul_f32 v[32:33], v[32:33], v[34:35] op_sel_hi:[1,0]
	v_pk_mul_f32 v[30:31], v[30:31], v[34:35] op_sel_hi:[1,0]
	v_pk_mul_f32 v[28:29], v[28:29], v[34:35] op_sel_hi:[1,0]
	v_pk_mul_f32 v[26:27], v[26:27], v[34:35] op_sel_hi:[1,0]
	v_pk_mul_f32 v[24:25], v[24:25], v[34:35] op_sel_hi:[1,0]
	v_pk_mul_f32 v[22:23], v[22:23], v[34:35] op_sel_hi:[1,0]
	v_pk_mul_f32 v[20:21], v[20:21], v[34:35] op_sel_hi:[1,0]
	v_pk_mul_f32 v[18:19], v[18:19], v[34:35] op_sel_hi:[1,0]
	v_pk_mul_f32 v[16:17], v[16:17], v[34:35] op_sel_hi:[1,0]
	v_pk_mul_f32 v[14:15], v[14:15], v[34:35] op_sel_hi:[1,0]
	v_pk_mul_f32 v[12:13], v[12:13], v[34:35] op_sel_hi:[1,0]
	v_pk_mul_f32 v[10:11], v[10:11], v[34:35] op_sel_hi:[1,0]
	v_pk_mul_f32 v[8:9], v[8:9], v[34:35] op_sel_hi:[1,0]
	v_pk_mul_f32 v[6:7], v[6:7], v[34:35] op_sel_hi:[1,0]
	v_pk_mul_f32 v[4:5], v[4:5], v[34:35] op_sel_hi:[1,0]
	v_pk_mul_f32 v[2:3], v[2:3], v[34:35] op_sel_hi:[1,0]
	v_mul_f32_e32 v97, v97, v34
